# speedup vs baseline: 1.0097x; 1.0004x over previous
; __device__ __forceinline__ void finishSM(f32x16& p0, f32x16& p1, float alpha, float& l_reg, bf16x8& pa0, bf16x8& pa1, bf16x8& pa2, bf16x8& pa3) {
; #pragma unroll
;   for (int r = 0; r < 16; ++r) p1[r] = __builtin_amdgcn_exp2f(p1[r]);
;   float ps = 0;
; #pragma unroll
;   for (int r = 0; r < 16; ++r) ps += p0[r];
; #pragma unroll
;   for (int r = 0; r < 16; ++r) ps += p1[r];
;   { auto rr = __builtin_amdgcn_permlane32_swap(__float_as_uint(ps), __float_as_uint(ps), false, false);
;     ps = __uint_as_float(rr[0]) + __uint_as_float(rr[1]); }
;   l_reg = l_reg * alpha + ps;
;     ...
;   PK4(p0, 0, pa0); PK4(p0, 8, pa1); PK4(p1, 0, pa2); PK4(p1, 8, pa3);
;     ...
; }
; template <int BUFOFF>
; __device__ __forceinline__ void qkt_mla(f32x16& p0, f32x16& p1, const int* ka, const bf16x8* qr, const char* qlds) {
;   typedef __attribute__((address_space(3))) const bf16x8* lp;
;   p0 = f32x16{}; p1 = f32x16{};
; #pragma unroll
;   for (int d0 = 0; d0 < 12; ++d0) {
;     const int a = ka[d0 & 3] + (d0 >> 2) * 128 + BUFOFF;
;     const bf16x8 b0 = *(lp)(a), b1 = *(lp)(a + 12288);
;     bf16x8 qf;
;     qf = qr[d0];
;     p0 = __builtin_amdgcn_mfma_f32_32x32x16_bf16(b0, qf, p0, 0, 0, 0);
;     p1 = __builtin_amdgcn_mfma_f32_32x32x16_bf16(b1, qf, p1, 0, 0, 0);
;   }
; }
.LBB0_115:
	s_mov_b32 s55, s43
	s_mov_b32 s43, s52
	ds_read_b128 v[64:67], v169 offset:24576
	ds_read_b128 v[68:71], v169 offset:36864
	ds_read_b128 v[214:217], v190 offset:24576
	ds_read_b128 v[218:221], v190 offset:36864
	s_waitcnt lgkmcnt(0)
	v_mfma_f32_32x32x16_bf16 v[80:95], v[64:67], v[140:143], v[226:241]
	v_add_f32_e32 v144, v200, v145
	v_mfma_f32_32x32x16_bf16 v[64:79], v[68:71], v[140:143], v[226:241]
	v_add_f32_e32 v243, v203, v210
	v_add_f32_e32 v244, v202, v208
	v_add_f32_e32 v245, v205, v212
	v_add_f32_e32 v246, v199, v211
	v_add_f32_e32 v247, v201, v213
	v_mfma_f32_32x32x16_bf16 v[80:95], v[214:217], v[136:139], v[80:95]
	v_add_f32_e32 v251, v204, v207
	v_add_f32_e32 v252, v206, v209
	v_mov_b32_e32 v196, v158
	v_add_f32_e32 v144, v172, v144
	v_add_f32_e32 v243, v173, v243
	v_mfma_f32_32x32x16_bf16 v[64:79], v[218:221], v[136:139], v[64:79]
	ds_read_b128 v[214:217], v193 offset:24576
	ds_read_b128 v[218:221], v193 offset:36864
	v_add_f32_e32 v244, v170, v244
	v_add_f32_e32 v245, v171, v245
	v_add_f32_e32 v246, v158, v246
	v_mov_b32_e32 v222, v147
	v_mov_b32_e32 v223, v154
	v_mov_b32_e32 v224, v155
	s_waitcnt lgkmcnt(0)
	v_mfma_f32_32x32x16_bf16 v[80:95], v[214:217], v[132:135], v[80:95]
	v_mfma_f32_32x32x16_bf16 v[64:79], v[218:221], v[132:135], v[64:79]
	ds_read_b128 v[214:217], v192 offset:24576
	ds_read_b128 v[218:221], v192 offset:36864
	s_waitcnt lgkmcnt(0)
	v_mfma_f32_32x32x16_bf16 v[80:95], v[214:217], v[128:131], v[80:95]
	v_mfma_f32_32x32x16_bf16 v[64:79], v[218:221], v[128:131], v[64:79]
	ds_read_b128 v[214:217], v169 offset:24704
	ds_read_b128 v[218:221], v169 offset:36992
	s_waitcnt lgkmcnt(0)
	v_mfma_f32_32x32x16_bf16 v[80:95], v[214:217], v[124:127], v[80:95]
	v_mfma_f32_32x32x16_bf16 v[64:79], v[218:221], v[124:127], v[64:79]
	ds_read_b128 v[214:217], v190 offset:24704
	ds_read_b128 v[218:221], v190 offset:36992
	s_waitcnt lgkmcnt(0)
	v_mfma_f32_32x32x16_bf16 v[80:95], v[214:217], v[120:123], v[80:95]
	v_mfma_f32_32x32x16_bf16 v[64:79], v[218:221], v[120:123], v[64:79]
	ds_read_b128 v[214:217], v193 offset:24704
	ds_read_b128 v[218:221], v193 offset:36992
	s_waitcnt lgkmcnt(0)
	v_mfma_f32_32x32x16_bf16 v[80:95], v[214:217], v[116:119], v[80:95]
	v_mfma_f32_32x32x16_bf16 v[64:79], v[218:221], v[116:119], v[64:79]
	ds_read_b128 v[214:217], v192 offset:24704
	ds_read_b128 v[218:221], v192 offset:36992
	s_waitcnt lgkmcnt(0)
	v_mfma_f32_32x32x16_bf16 v[80:95], v[214:217], v[112:115], v[80:95]
	v_mfma_f32_32x32x16_bf16 v[64:79], v[218:221], v[112:115], v[64:79]
	ds_read_b128 v[214:217], v169 offset:24832
	ds_read_b128 v[218:221], v169 offset:37120
	s_waitcnt lgkmcnt(0)
	v_mfma_f32_32x32x16_bf16 v[80:95], v[214:217], v[108:111], v[80:95]
	v_mfma_f32_32x32x16_bf16 v[64:79], v[218:221], v[108:111], v[64:79]
	ds_read_b128 v[214:217], v190 offset:24832
	ds_read_b128 v[218:221], v190 offset:37120
	s_waitcnt lgkmcnt(0)
	v_mfma_f32_32x32x16_bf16 v[80:95], v[214:217], v[104:107], v[80:95]
	v_mfma_f32_32x32x16_bf16 v[64:79], v[218:221], v[104:107], v[64:79]
	ds_read_b128 v[214:217], v193 offset:24832
	ds_read_b128 v[218:221], v193 offset:37120
	s_waitcnt lgkmcnt(0)
	v_mfma_f32_32x32x16_bf16 v[80:95], v[214:217], v[100:103], v[80:95]
	v_mfma_f32_32x32x16_bf16 v[64:79], v[218:221], v[100:103], v[64:79]
	ds_read_b128 v[214:217], v192 offset:24832
	ds_read_b128 v[218:221], v192 offset:37120
	s_waitcnt lgkmcnt(0)
	v_mfma_f32_32x32x16_bf16 v[80:95], v[214:217], v[96:99], v[80:95]
	v_mov_b32_e32 v214, v159
	v_mov_b32_e32 v215, v152
	v_mov_b32_e32 v216, v153
	v_mov_b32_e32 v217, v150
	v_add_f32_e32 v247, v159, v247
	v_add_f32_e32 v251, v152, v251
	v_add_f32_e32 v252, v153, v252
	v_mfma_f32_32x32x16_bf16 v[64:79], v[218:221], v[96:99], v[64:79]
	v_mov_b32_e32 v218, v151
	v_mov_b32_e32 v219, v148
	v_mov_b32_e32 v220, v149
	v_mov_b32_e32 v221, v146
	v_add_f32_e32 v144, v150, v144
	v_add_f32_e32 v243, v151, v243
	v_add_f32_e32 v244, v148, v244
	v_add_f32_e32 v245, v149, v245
	v_add_f32_e32 v246, v146, v246
	v_add_f32_e32 v247, v147, v247
	v_add_f32_e32 v251, v154, v251
	v_add_f32_e32 v252, v155, v252
	v_add_f32_e32 v144, v144, v243
	v_add_f32_e32 v244, v244, v245
	v_add_f32_e32 v246, v246, v247
	v_add_f32_e32 v251, v251, v252
	v_add_f32_e32 v144, v144, v244
	v_add_f32_e32 v246, v246, v251
	v_add_f32_e32 v158, v144, v246
	v_mov_b32_e32 v159, v158
	v_cvt_pk_bf16_f32 v144, v145, v210
	v_cvt_pk_bf16_f32 v145, v208, v212
	v_cvt_pk_bf16_f32 v146, v211, v213
	v_cvt_pk_bf16_f32 v147, v207, v209
	v_cvt_pk_bf16_f32 v148, v200, v203
	v_cvt_pk_bf16_f32 v149, v202, v205
	v_cvt_pk_bf16_f32 v150, v199, v201
	v_cvt_pk_bf16_f32 v151, v204, v206
	v_cvt_pk_bf16_f32 v152, v172, v173
	v_cvt_pk_bf16_f32 v153, v170, v171
	v_cvt_pk_bf16_f32 v154, v196, v214
	s_nop 1
	v_permlane32_swap_b32_e32 v158, v159
	v_cvt_pk_bf16_f32 v155, v215, v216
	v_cvt_pk_bf16_f32 v170, v217, v218
	v_cvt_pk_bf16_f32 v171, v219, v220
	v_cvt_pk_bf16_f32 v172, v221, v222
	v_cvt_pk_bf16_f32 v173, v223, v224
	v_readlane_b32 s58, v249, 37
	v_readlane_b32 s59, v249, 38
	s_add_u32 s56, s58, s47
	s_addc_u32 s57, s59, s50
	s_add_u32 s4, s56, 0x17060000
	s_addc_u32 s5, s57, 0
	s_add_u32 s58, s58, s14
	s_addc_u32 s59, s59, s15
	s_add_u32 s60, s58, 0x1a040000
	s_mov_b32 m0, s41
	s_addc_u32 s61, s59, 0
	s_lshl_b32 s52, s54, 14
	s_add_i32 s62, s40, s52
	global_load_lds_dwordx4 v188, s[4:5]
	s_mov_b32 m0, s42
	s_nop 0
	global_load_lds_dwordx4 v189, s[4:5]
	s_add_i32 m0, s41, 0x4000
	s_nop 0
	global_load_lds_dwordx4 v191, s[4:5]
	s_mov_b32 m0, s62
	s_nop 0
	global_load_lds_dwordx4 v194, s[60:61]
	s_add_i32 m0, s62, 0x2000
	s_nop 0
	global_load_lds_dwordx4 v195, s[60:61]
	s_lshl_b32 s60, s43, 14
	v_add_u32_e32 v196, s60, v167
	ds_read_b64_tr_b16 v[200:201], v196 offset:0
	ds_read_b64_tr_b16 v[202:203], v196 offset:0x800
	ds_read_b64_tr_b16 v[204:205], v196 offset:0x1000
	ds_read_b64_tr_b16 v[206:207], v196 offset:0x1800
	ds_read_b64_tr_b16 v[208:209], v196 offset:0x2000
	ds_read_b64_tr_b16 v[210:211], v196 offset:0x2800
	ds_read_b64_tr_b16 v[212:213], v196 offset:0x3000
	ds_read_b64_tr_b16 v[214:215], v196 offset:0x3800
	s_nop 0
	s_waitcnt lgkmcnt(6)
; #define SBAR() __builtin_amdgcn_sched_barrier(0)
; template <int MLA>
; __device__ __forceinline__ void partialSM(f32x16& p0, f32x16& p1, float& m_reg, float& mn, float& alpha) {
;   constexpr float SCALE = AttC<MLA>::SCALE;
;   constexpr float C = SCALE * 1.4426950408889634f;
;   float pmax = p0[0];
; #pragma unroll
;   for (int r = 1; r < 16; ++r) pmax = fmaxf(pmax, p0[r]);
; #pragma unroll
;   for (int r = 0; r < 16; ++r) pmax = fmaxf(pmax, p1[r]);
;   { auto rr = __builtin_amdgcn_permlane32_swap(__float_as_uint(pmax), __float_as_uint(pmax), false, false);
;     pmax = fmaxf(__uint_as_float(rr[0]), __uint_as_float(rr[1])); }
;   if (__builtin_expect(__all(pmax - m_reg <= THR / SCALE), 1)) { mn = m_reg; alpha = 1.f; }
;   else { mn = fmaxf(m_reg, pmax); alpha = __builtin_amdgcn_exp2f((m_reg - mn) * C); m_reg = mn; }
;   float mnC = -mn * C;
; #pragma unroll
;   for (int r = 0; r < 16; ++r) p0[r] = fmaf(p0[r], C, mnC);
; #pragma unroll
;   for (int r = 0; r < 16; ++r) p1[r] = fmaf(p1[r], C, mnC);
; #pragma unroll
;   for (int r = 0; r < 16; ++r) p0[r] = __builtin_amdgcn_exp2f(p0[r]);
; }
; template <int D0> __device__ __forceinline__ void pv_one_t(f32x16& od, int vb, bf16x8 pa0, bf16x8 pa1, bf16x8 pa2, bf16x8 pa3) {
;   const s16x4 l0 = tr_read<v_rd_off(D0, 0, 0)>(vb), h0 = tr_read<v_rd_off(D0, 0, 1)>(vb), l1 = tr_read<v_rd_off(D0, 1, 0)>(vb), h1 = tr_read<v_rd_off(D0, 1, 1)>(vb);
;   const s16x4 l2 = tr_read<v_rd_off(D0, 2, 0)>(vb), h2 = tr_read<v_rd_off(D0, 2, 1)>(vb), l3 = tr_read<v_rd_off(D0, 3, 0)>(vb), h3 = tr_read<v_rd_off(D0, 3, 1)>(vb);
;   asm volatile("s_waitcnt lgkmcnt(0)" ::: "memory"); SBAR();
;     ...
;   od = __builtin_amdgcn_mfma_f32_32x32x16_bf16(PK(l0, h0), pa0, od, 0, 0, 0);
;   od = __builtin_amdgcn_mfma_f32_32x32x16_bf16(PK(l1, h1), pa1, od, 0, 0, 0);
;   od = __builtin_amdgcn_mfma_f32_32x32x16_bf16(PK(l2, h2), pa2, od, 0, 0, 0);
;   od = __builtin_amdgcn_mfma_f32_32x32x16_bf16(PK(l3, h3), pa3, od, 0, 0, 0);
;     ...
; }
; __device__ __forceinline__ void pv_d0_t(f32x16* o, int vb, bf16x8 pa0, bf16x8 pa1, bf16x8 pa2, bf16x8 pa3) {
;   pv_one_t<0>(o[0], vb, pa0, pa1, pa2, pa3); pv_one_t<1>(o[1], vb, pa0, pa1, pa2, pa3); pv_one_t<2>(o[2], vb, pa0, pa1, pa2, pa3); pv_one_t<3>(o[3], vb, pa0, pa1, pa2, pa3);
; }
	v_mfma_f32_32x32x16_bf16 v[0:15], v[200:203], v[144:147], v[0:15]
	ds_read_b64_tr_b16 v[200:201], v196 offset:0x200
	ds_read_b64_tr_b16 v[202:203], v196 offset:0xa00
	s_waitcnt lgkmcnt(6)
	v_mfma_f32_32x32x16_bf16 v[0:15], v[204:207], v[148:151], v[0:15]
	ds_read_b64_tr_b16 v[204:205], v196 offset:0x1200
	ds_read_b64_tr_b16 v[206:207], v196 offset:0x1a00
	s_waitcnt lgkmcnt(6)
	v_mfma_f32_32x32x16_bf16 v[0:15], v[208:211], v[152:155], v[0:15]
	ds_read_b64_tr_b16 v[208:209], v196 offset:0x2200
	ds_read_b64_tr_b16 v[210:211], v196 offset:0x2a00
	s_waitcnt lgkmcnt(6)
	v_mfma_f32_32x32x16_bf16 v[0:15], v[212:215], v[170:173], v[0:15]
	ds_read_b64_tr_b16 v[212:213], v196 offset:0x3200
	ds_read_b64_tr_b16 v[214:215], v196 offset:0x3a00
	s_waitcnt lgkmcnt(6)
	v_mfma_f32_32x32x16_bf16 v[48:63], v[200:203], v[144:147], v[48:63]
	ds_read_b64_tr_b16 v[200:201], v196 offset:0x400
	ds_read_b64_tr_b16 v[202:203], v196 offset:0xc00
	s_waitcnt lgkmcnt(6)
	v_mfma_f32_32x32x16_bf16 v[48:63], v[204:207], v[148:151], v[48:63]
	ds_read_b64_tr_b16 v[204:205], v196 offset:0x1400
	ds_read_b64_tr_b16 v[206:207], v196 offset:0x1c00
	s_waitcnt lgkmcnt(6)
	v_mfma_f32_32x32x16_bf16 v[48:63], v[208:211], v[152:155], v[48:63]
	ds_read_b64_tr_b16 v[208:209], v196 offset:0x2400
	ds_read_b64_tr_b16 v[210:211], v196 offset:0x2c00
	s_waitcnt lgkmcnt(6)
	v_mfma_f32_32x32x16_bf16 v[48:63], v[212:215], v[170:173], v[48:63]
	ds_read_b64_tr_b16 v[212:213], v196 offset:0x3400
	ds_read_b64_tr_b16 v[214:215], v196 offset:0x3c00
	s_waitcnt lgkmcnt(6)
	v_mfma_f32_32x32x16_bf16 v[32:47], v[200:203], v[144:147], v[32:47]
	ds_read_b64_tr_b16 v[200:201], v196 offset:0x600
	ds_read_b64_tr_b16 v[202:203], v196 offset:0xe00
	s_waitcnt lgkmcnt(6)
	v_mfma_f32_32x32x16_bf16 v[32:47], v[204:207], v[148:151], v[32:47]
	ds_read_b64_tr_b16 v[204:205], v196 offset:0x1600
	ds_read_b64_tr_b16 v[206:207], v196 offset:0x1e00
	s_waitcnt lgkmcnt(6)
	v_mfma_f32_32x32x16_bf16 v[32:47], v[208:211], v[152:155], v[32:47]
	ds_read_b64_tr_b16 v[208:209], v196 offset:0x2600
	ds_read_b64_tr_b16 v[210:211], v196 offset:0x2e00
	s_waitcnt lgkmcnt(6)
	v_mfma_f32_32x32x16_bf16 v[32:47], v[212:215], v[170:173], v[32:47]
	ds_read_b64_tr_b16 v[212:213], v196 offset:0x3600
	ds_read_b64_tr_b16 v[214:215], v196 offset:0x3e00
	s_waitcnt lgkmcnt(6)
	v_mfma_f32_32x32x16_bf16 v[16:31], v[200:203], v[144:147], v[16:31]
	v_max_f32_e32 v144, v80, v81
	v_max3_f32 v144, v144, v82, v83
	v_max3_f32 v144, v144, v84, v85
	v_max3_f32 v144, v144, v86, v87
	v_max3_f32 v144, v144, v88, v89
	v_max3_f32 v144, v144, v90, v91
	v_max3_f32 v144, v144, v92, v93
	s_waitcnt lgkmcnt(4)
	v_mfma_f32_32x32x16_bf16 v[16:31], v[204:207], v[148:151], v[16:31]
	v_max3_f32 v144, v144, v94, v95
	v_max3_f32 v144, v144, v64, v65
	v_max3_f32 v144, v144, v66, v67
	v_max3_f32 v144, v144, v68, v69
	v_max3_f32 v144, v144, v70, v71
	v_max3_f32 v144, v144, v72, v73
	v_max3_f32 v144, v144, v74, v75
	v_max3_f32 v144, v144, v76, v77
	s_waitcnt lgkmcnt(2)
	v_mfma_f32_32x32x16_bf16 v[16:31], v[208:211], v[152:155], v[16:31]
	v_max3_f32 v144, v144, v78, v79
	v_mov_b32_e32 v145, v144
	s_nop 1
	v_permlane32_swap_b32_e32 v144, v145
	v_max_f32_e32 v144, v144, v145
	v_cmp_ge_f32_e32 vcc, s63, v144
	s_waitcnt lgkmcnt(0)
	v_mfma_f32_32x32x16_bf16 v[16:31], v[212:215], v[170:173], v[16:31]
	s_cmp_eq_u64 vcc, exec
	s_cselect_b64 s[4:5], -1, 0
	s_waitcnt vmcnt(0) lgkmcnt(0)
	s_barrier
	s_cbranch_scc1 .Lal_c_m1
	v_max_f32_e32 v242, 0, v144
	v_exp_f32_e64 v152, -v242
	s_nop 0
	v_pk_mul_f32 v[14:15], v[14:15], v[152:153] op_sel_hi:[1,0]
	v_pk_mul_f32 v[12:13], v[12:13], v[152:153] op_sel_hi:[1,0]
	v_pk_mul_f32 v[10:11], v[10:11], v[152:153] op_sel_hi:[1,0]
	v_pk_mul_f32 v[8:9], v[8:9], v[152:153] op_sel_hi:[1,0]
	v_pk_mul_f32 v[6:7], v[6:7], v[152:153] op_sel_hi:[1,0]
	v_pk_mul_f32 v[4:5], v[4:5], v[152:153] op_sel_hi:[1,0]
	v_pk_mul_f32 v[2:3], v[2:3], v[152:153] op_sel_hi:[1,0]
	v_pk_mul_f32 v[0:1], v[0:1], v[152:153] op_sel_hi:[1,0]
	v_pk_mul_f32 v[62:63], v[62:63], v[152:153] op_sel_hi:[1,0]
	v_pk_mul_f32 v[60:61], v[60:61], v[152:153] op_sel_hi:[1,0]
	v_pk_mul_f32 v[58:59], v[58:59], v[152:153] op_sel_hi:[1,0]
	v_pk_mul_f32 v[56:57], v[56:57], v[152:153] op_sel_hi:[1,0]
	v_pk_mul_f32 v[54:55], v[54:55], v[152:153] op_sel_hi:[1,0]
	v_pk_mul_f32 v[52:53], v[52:53], v[152:153] op_sel_hi:[1,0]
	v_pk_mul_f32 v[50:51], v[50:51], v[152:153] op_sel_hi:[1,0]
	v_pk_mul_f32 v[48:49], v[48:49], v[152:153] op_sel_hi:[1,0]
	v_pk_mul_f32 v[46:47], v[46:47], v[152:153] op_sel_hi:[1,0]
	v_pk_mul_f32 v[44:45], v[44:45], v[152:153] op_sel_hi:[1,0]
	v_pk_mul_f32 v[42:43], v[42:43], v[152:153] op_sel_hi:[1,0]
	v_pk_mul_f32 v[40:41], v[40:41], v[152:153] op_sel_hi:[1,0]
	v_pk_mul_f32 v[38:39], v[38:39], v[152:153] op_sel_hi:[1,0]
	v_pk_mul_f32 v[36:37], v[36:37], v[152:153] op_sel_hi:[1,0]
	v_pk_mul_f32 v[34:35], v[34:35], v[152:153] op_sel_hi:[1,0]
	v_pk_mul_f32 v[32:33], v[32:33], v[152:153] op_sel_hi:[1,0]
	v_pk_mul_f32 v[30:31], v[30:31], v[152:153] op_sel_hi:[1,0]
	v_pk_mul_f32 v[28:29], v[28:29], v[152:153] op_sel_hi:[1,0]
	v_pk_mul_f32 v[26:27], v[26:27], v[152:153] op_sel_hi:[1,0]
	v_pk_mul_f32 v[24:25], v[24:25], v[152:153] op_sel_hi:[1,0]
	v_pk_mul_f32 v[22:23], v[22:23], v[152:153] op_sel_hi:[1,0]
	v_pk_mul_f32 v[20:21], v[20:21], v[152:153] op_sel_hi:[1,0]
	v_pk_mul_f32 v[18:19], v[18:19], v[152:153] op_sel_hi:[1,0]
	v_pk_mul_f32 v[16:17], v[16:17], v[152:153] op_sel_hi:[1,0]
	v_sub_f32_e32 v80, v80, v242
	v_sub_f32_e32 v81, v81, v242
	v_sub_f32_e32 v82, v82, v242
	v_sub_f32_e32 v83, v83, v242
	v_sub_f32_e32 v84, v84, v242
	v_sub_f32_e32 v85, v85, v242
	v_sub_f32_e32 v86, v86, v242
	v_sub_f32_e32 v87, v87, v242
	v_sub_f32_e32 v88, v88, v242
	v_sub_f32_e32 v89, v89, v242
	v_sub_f32_e32 v90, v90, v242
	v_sub_f32_e32 v91, v91, v242
	v_sub_f32_e32 v92, v92, v242
	v_sub_f32_e32 v93, v93, v242
	v_sub_f32_e32 v94, v94, v242
	v_sub_f32_e32 v95, v95, v242
	v_sub_f32_e32 v64, v64, v242
	v_sub_f32_e32 v65, v65, v242
	v_sub_f32_e32 v66, v66, v242
	v_sub_f32_e32 v67, v67, v242
	v_sub_f32_e32 v68, v68, v242
	v_sub_f32_e32 v69, v69, v242
	v_sub_f32_e32 v70, v70, v242
	v_sub_f32_e32 v71, v71, v242
	v_sub_f32_e32 v72, v72, v242
	v_sub_f32_e32 v73, v73, v242
	v_sub_f32_e32 v74, v74, v242
	v_sub_f32_e32 v75, v75, v242
	v_sub_f32_e32 v76, v76, v242
	v_sub_f32_e32 v77, v77, v242
	v_sub_f32_e32 v78, v78, v242
	v_sub_f32_e32 v79, v79, v242
	v_sub_f32_e32 v226, v226, v242
	v_sub_f32_e32 v227, v227, v242
	v_sub_f32_e32 v228, v228, v242
	v_sub_f32_e32 v229, v229, v242
	v_sub_f32_e32 v230, v230, v242
	v_sub_f32_e32 v231, v231, v242
	v_sub_f32_e32 v232, v232, v242
	v_sub_f32_e32 v233, v233, v242
	v_sub_f32_e32 v234, v234, v242
	v_sub_f32_e32 v235, v235, v242
	v_sub_f32_e32 v236, v236, v242
	v_sub_f32_e32 v237, v237, v242
	v_sub_f32_e32 v238, v238, v242
	v_sub_f32_e32 v239, v239, v242
	v_sub_f32_e32 v240, v240, v242
	v_sub_f32_e32 v241, v241, v242
	s_branch .LBB0_117

; __device__ __forceinline__ void finishSM(f32x16& p0, f32x16& p1, float alpha, float& l_reg, bf16x8& pa0, bf16x8& pa1, bf16x8& pa2, bf16x8& pa3) {
; #pragma unroll
;   for (int r = 0; r < 16; ++r) p1[r] = __builtin_amdgcn_exp2f(p1[r]);
;   float ps = 0;
; #pragma unroll
;   for (int r = 0; r < 16; ++r) ps += p0[r];
; #pragma unroll
;   for (int r = 0; r < 16; ++r) ps += p1[r];
;   { auto rr = __builtin_amdgcn_permlane32_swap(__float_as_uint(ps), __float_as_uint(ps), false, false);
;     ps = __uint_as_float(rr[0]) + __uint_as_float(rr[1]); }
;   l_reg = l_reg * alpha + ps;
;     ...
;   PK4(p0, 0, pa0); PK4(p0, 8, pa1); PK4(p1, 0, pa2); PK4(p1, 8, pa3);
;     ...
; }
; template <int BUFOFF>
; __device__ __forceinline__ void qkt_mla(f32x16& p0, f32x16& p1, const int* ka, const bf16x8* qr, const char* qlds) {
;   typedef __attribute__((address_space(3))) const bf16x8* lp;
;   p0 = f32x16{}; p1 = f32x16{};
; #pragma unroll
;   for (int d0 = 0; d0 < 12; ++d0) {
;     const int a = ka[d0 & 3] + (d0 >> 2) * 128 + BUFOFF;
;     const bf16x8 b0 = *(lp)(a), b1 = *(lp)(a + 12288);
;     bf16x8 qf;
;     qf = qr[d0];
;     p0 = __builtin_amdgcn_mfma_f32_32x32x16_bf16(b0, qf, p0, 0, 0, 0);
;     p1 = __builtin_amdgcn_mfma_f32_32x32x16_bf16(b1, qf, p1, 0, 0, 0);
;   }
; }
.LBB0_117:
	v_exp_f32_e32 v155, v64
	v_exp_f32_e32 v170, v65
	v_exp_f32_e32 v171, v66
	v_exp_f32_e32 v172, v67
	v_exp_f32_e32 v173, v68
	v_exp_f32_e32 v197, v69
	v_exp_f32_e32 v199, v70
	v_exp_f32_e32 v200, v71
	v_exp_f32_e32 v201, v72
	v_exp_f32_e32 v202, v73
	v_exp_f32_e32 v203, v74
	v_exp_f32_e32 v204, v75
	v_exp_f32_e32 v205, v76
	v_exp_f32_e32 v222, v77
	v_exp_f32_e32 v223, v78
	v_exp_f32_e32 v154, v79
	v_exp_f32_e32 v206, v80
	v_exp_f32_e32 v207, v81
	v_exp_f32_e32 v208, v82
	v_exp_f32_e32 v209, v83
	v_exp_f32_e32 v210, v84
	v_exp_f32_e32 v211, v85
	v_exp_f32_e32 v212, v86
	v_exp_f32_e32 v213, v87
	v_exp_f32_e32 v214, v88
	v_exp_f32_e32 v215, v89
	v_exp_f32_e32 v216, v90
	v_exp_f32_e32 v217, v91
	v_exp_f32_e32 v218, v92
	v_exp_f32_e32 v219, v93
	v_exp_f32_e32 v220, v94
	v_exp_f32_e32 v221, v95
	ds_read_b128 v[64:67], v169
	ds_read_b128 v[68:71], v169 offset:12288
	ds_read_b128 v[144:147], v190
	ds_read_b128 v[148:151], v190 offset:12288
	v_mov_b32_e32 v224, v155
	s_waitcnt lgkmcnt(0)
	v_mfma_f32_32x32x16_bf16 v[80:95], v[64:67], v[140:143], v[226:241]
	v_mfma_f32_32x32x16_bf16 v[64:79], v[68:71], v[140:143], v[226:241]
	v_mov_b32_e32 v225, v154
	v_mfma_f32_32x32x16_bf16 v[80:95], v[144:147], v[136:139], v[80:95]
	v_mfma_f32_32x32x16_bf16 v[64:79], v[148:151], v[136:139], v[64:79]
	ds_read_b128 v[144:147], v193
	ds_read_b128 v[148:151], v193 offset:12288
	s_waitcnt lgkmcnt(0)
	v_mfma_f32_32x32x16_bf16 v[80:95], v[144:147], v[132:135], v[80:95]
	v_mfma_f32_32x32x16_bf16 v[64:79], v[148:151], v[132:135], v[64:79]
	ds_read_b128 v[144:147], v192
	ds_read_b128 v[148:151], v192 offset:12288
	s_waitcnt lgkmcnt(0)
	v_mfma_f32_32x32x16_bf16 v[80:95], v[144:147], v[128:131], v[80:95]
	v_mfma_f32_32x32x16_bf16 v[64:79], v[148:151], v[128:131], v[64:79]
	ds_read_b128 v[144:147], v169 offset:128
	ds_read_b128 v[148:151], v169 offset:12416
	s_waitcnt lgkmcnt(0)
	v_mfma_f32_32x32x16_bf16 v[80:95], v[144:147], v[124:127], v[80:95]
	v_mfma_f32_32x32x16_bf16 v[64:79], v[148:151], v[124:127], v[64:79]
	ds_read_b128 v[144:147], v190 offset:128
	ds_read_b128 v[148:151], v190 offset:12416
	s_waitcnt lgkmcnt(0)
	v_mfma_f32_32x32x16_bf16 v[80:95], v[144:147], v[120:123], v[80:95]
	v_mfma_f32_32x32x16_bf16 v[64:79], v[148:151], v[120:123], v[64:79]
	ds_read_b128 v[144:147], v193 offset:128
	ds_read_b128 v[148:151], v193 offset:12416
	s_waitcnt lgkmcnt(0)
	v_mfma_f32_32x32x16_bf16 v[80:95], v[144:147], v[116:119], v[80:95]
	v_mfma_f32_32x32x16_bf16 v[64:79], v[148:151], v[116:119], v[64:79]
	ds_read_b128 v[144:147], v192 offset:128
	ds_read_b128 v[148:151], v192 offset:12416
	s_waitcnt lgkmcnt(0)
	v_mfma_f32_32x32x16_bf16 v[80:95], v[144:147], v[112:115], v[80:95]
	v_mfma_f32_32x32x16_bf16 v[64:79], v[148:151], v[112:115], v[64:79]
	ds_read_b128 v[144:147], v169 offset:256
	ds_read_b128 v[148:151], v169 offset:12544
	s_waitcnt lgkmcnt(0)
	v_mfma_f32_32x32x16_bf16 v[80:95], v[144:147], v[108:111], v[80:95]
	v_mfma_f32_32x32x16_bf16 v[64:79], v[148:151], v[108:111], v[64:79]
	ds_read_b128 v[144:147], v190 offset:256
	ds_read_b128 v[148:151], v190 offset:12544
	s_waitcnt lgkmcnt(0)
	v_mfma_f32_32x32x16_bf16 v[80:95], v[144:147], v[104:107], v[80:95]
	v_mfma_f32_32x32x16_bf16 v[64:79], v[148:151], v[104:107], v[64:79]
	ds_read_b128 v[144:147], v193 offset:256
	ds_read_b128 v[148:151], v193 offset:12544
	s_waitcnt lgkmcnt(0)
	v_mfma_f32_32x32x16_bf16 v[80:95], v[144:147], v[100:103], v[80:95]
	v_mfma_f32_32x32x16_bf16 v[64:79], v[148:151], v[100:103], v[64:79]
	ds_read_b128 v[144:147], v192 offset:256
	ds_read_b128 v[148:151], v192 offset:12544
	s_waitcnt lgkmcnt(0)
	v_mfma_f32_32x32x16_bf16 v[80:95], v[144:147], v[96:99], v[80:95]
	v_add_f32_e32 v144, v214, v206
	v_add_f32_e32 v243, v215, v207
	v_add_f32_e32 v244, v216, v208
	v_add_f32_e32 v245, v217, v209
	v_add_f32_e32 v246, v218, v210
	v_add_f32_e32 v247, v219, v211
	v_add_f32_e32 v251, v220, v212
	v_add_f32_e32 v252, v221, v213
	v_add_f32_e32 v144, v155, v144
	v_add_f32_e32 v243, v170, v243
	v_add_f32_e32 v244, v171, v244
	v_add_f32_e32 v245, v172, v245
	v_add_f32_e32 v246, v173, v246
	v_add_f32_e32 v247, v197, v247
	v_add_f32_e32 v251, v199, v251
	v_add_f32_e32 v252, v200, v252
	v_add_f32_e32 v144, v201, v144
	v_add_f32_e32 v243, v202, v243
	v_mfma_f32_32x32x16_bf16 v[64:79], v[148:151], v[96:99], v[64:79]
	v_add_f32_e32 v244, v203, v244
	v_add_f32_e32 v245, v204, v245
	v_add_f32_e32 v246, v205, v246
	v_add_f32_e32 v247, v222, v247
	v_add_f32_e32 v251, v223, v251
	v_add_f32_e32 v252, v154, v252
	v_add_f32_e32 v144, v144, v243
	v_add_f32_e32 v244, v244, v245
	v_add_f32_e32 v246, v246, v247
	v_add_f32_e32 v251, v251, v252
	v_add_f32_e32 v144, v144, v244
	v_add_f32_e32 v246, v246, v251
	v_add_f32_e32 v154, v144, v246
	v_mov_b32_e32 v155, v154
	v_cvt_pk_bf16_f32 v144, v206, v207
	v_cvt_pk_bf16_f32 v145, v208, v209
	v_cvt_pk_bf16_f32 v146, v210, v211
	v_cvt_pk_bf16_f32 v147, v212, v213
	s_nop 1
	v_permlane32_swap_b32_e32 v154, v155
	v_cvt_pk_bf16_f32 v148, v214, v215
	v_cvt_pk_bf16_f32 v149, v216, v217
	v_cvt_pk_bf16_f32 v150, v218, v219
	v_cvt_pk_bf16_f32 v151, v220, v221
	v_cvt_pk_bf16_f32 v170, v224, v170
	v_cvt_pk_bf16_f32 v171, v171, v172
	v_cvt_pk_bf16_f32 v172, v173, v197
	v_cvt_pk_bf16_f32 v173, v199, v200
	v_cvt_pk_bf16_f32 v200, v201, v202
	v_cvt_pk_bf16_f32 v201, v203, v204
	v_cvt_pk_bf16_f32 v202, v205, v222
	v_cvt_pk_bf16_f32 v203, v223, v225
	s_nop 0
	s_add_u32 s4, s56, 0x17090000
	s_addc_u32 s5, s57, 0
	s_add_u32 s56, s58, 0x1a060000
	s_mov_b32 m0, s16
	s_addc_u32 s57, s59, 0
	s_add_i32 s58, s40, s60
	global_load_lds_dwordx4 v188, s[4:5]
	s_mov_b32 m0, s17
	s_nop 0
	global_load_lds_dwordx4 v189, s[4:5]
	s_mov_b32 m0, s44
	s_nop 0
	global_load_lds_dwordx4 v191, s[4:5]
	s_mov_b32 m0, s58
	s_nop 0
	global_load_lds_dwordx4 v194, s[56:57]
	s_add_i32 m0, s58, 0x2000
	s_nop 0
	global_load_lds_dwordx4 v195, s[56:57]
	v_lshl_add_u32 v197, s55, 14, v167
	ds_read_b64_tr_b16 v[204:205], v197 offset:0
	ds_read_b64_tr_b16 v[206:207], v197 offset:0x800
	ds_read_b64_tr_b16 v[208:209], v197 offset:0x1000
	ds_read_b64_tr_b16 v[210:211], v197 offset:0x1800
	ds_read_b64_tr_b16 v[212:213], v197 offset:0x2000
	ds_read_b64_tr_b16 v[214:215], v197 offset:0x2800
	ds_read_b64_tr_b16 v[216:217], v197 offset:0x3000
	ds_read_b64_tr_b16 v[218:219], v197 offset:0x3800
	s_nop 0
	s_waitcnt lgkmcnt(6)
; #define SBAR() __builtin_amdgcn_sched_barrier(0)
; template <int MLA>
; __device__ __forceinline__ void partialSM(f32x16& p0, f32x16& p1, float& m_reg, float& mn, float& alpha) {
;   constexpr float SCALE = AttC<MLA>::SCALE;
;   constexpr float C = SCALE * 1.4426950408889634f;
;   float pmax = p0[0];
; #pragma unroll
;   for (int r = 1; r < 16; ++r) pmax = fmaxf(pmax, p0[r]);
; #pragma unroll
;   for (int r = 0; r < 16; ++r) pmax = fmaxf(pmax, p1[r]);
;   { auto rr = __builtin_amdgcn_permlane32_swap(__float_as_uint(pmax), __float_as_uint(pmax), false, false);
;     pmax = fmaxf(__uint_as_float(rr[0]), __uint_as_float(rr[1])); }
;   if (__builtin_expect(__all(pmax - m_reg <= THR / SCALE), 1)) { mn = m_reg; alpha = 1.f; }
;   else { mn = fmaxf(m_reg, pmax); alpha = __builtin_amdgcn_exp2f((m_reg - mn) * C); m_reg = mn; }
;   float mnC = -mn * C;
; #pragma unroll
;   for (int r = 0; r < 16; ++r) p0[r] = fmaf(p0[r], C, mnC);
; #pragma unroll
;   for (int r = 0; r < 16; ++r) p1[r] = fmaf(p1[r], C, mnC);
; #pragma unroll
;   for (int r = 0; r < 16; ++r) p0[r] = __builtin_amdgcn_exp2f(p0[r]);
; }
; template <int D0> __device__ __forceinline__ void pv_one_t(f32x16& od, int vb, bf16x8 pa0, bf16x8 pa1, bf16x8 pa2, bf16x8 pa3) {
;   const s16x4 l0 = tr_read<v_rd_off(D0, 0, 0)>(vb), h0 = tr_read<v_rd_off(D0, 0, 1)>(vb), l1 = tr_read<v_rd_off(D0, 1, 0)>(vb), h1 = tr_read<v_rd_off(D0, 1, 1)>(vb);
;   const s16x4 l2 = tr_read<v_rd_off(D0, 2, 0)>(vb), h2 = tr_read<v_rd_off(D0, 2, 1)>(vb), l3 = tr_read<v_rd_off(D0, 3, 0)>(vb), h3 = tr_read<v_rd_off(D0, 3, 1)>(vb);
;   asm volatile("s_waitcnt lgkmcnt(0)" ::: "memory"); SBAR();
;     ...
;   od = __builtin_amdgcn_mfma_f32_32x32x16_bf16(PK(l0, h0), pa0, od, 0, 0, 0);
;   od = __builtin_amdgcn_mfma_f32_32x32x16_bf16(PK(l1, h1), pa1, od, 0, 0, 0);
;   od = __builtin_amdgcn_mfma_f32_32x32x16_bf16(PK(l2, h2), pa2, od, 0, 0, 0);
;   od = __builtin_amdgcn_mfma_f32_32x32x16_bf16(PK(l3, h3), pa3, od, 0, 0, 0);
;     ...
; }
; __device__ __forceinline__ void pv_d0_t(f32x16* o, int vb, bf16x8 pa0, bf16x8 pa1, bf16x8 pa2, bf16x8 pa3) {
;   pv_one_t<0>(o[0], vb, pa0, pa1, pa2, pa3); pv_one_t<1>(o[1], vb, pa0, pa1, pa2, pa3); pv_one_t<2>(o[2], vb, pa0, pa1, pa2, pa3); pv_one_t<3>(o[3], vb, pa0, pa1, pa2, pa3);
; }
	v_mfma_f32_32x32x16_bf16 v[0:15], v[204:207], v[144:147], v[0:15]
	ds_read_b64_tr_b16 v[204:205], v197 offset:0x200
	ds_read_b64_tr_b16 v[206:207], v197 offset:0xa00
	s_waitcnt lgkmcnt(6)
	v_mfma_f32_32x32x16_bf16 v[0:15], v[208:211], v[148:151], v[0:15]
	ds_read_b64_tr_b16 v[208:209], v197 offset:0x1200
	ds_read_b64_tr_b16 v[210:211], v197 offset:0x1a00
	s_waitcnt lgkmcnt(6)
	v_mfma_f32_32x32x16_bf16 v[0:15], v[212:215], v[170:173], v[0:15]
	ds_read_b64_tr_b16 v[212:213], v197 offset:0x2200
	ds_read_b64_tr_b16 v[214:215], v197 offset:0x2a00
	s_waitcnt lgkmcnt(6)
	v_mfma_f32_32x32x16_bf16 v[0:15], v[216:219], v[200:203], v[0:15]
	ds_read_b64_tr_b16 v[216:217], v197 offset:0x3200
	ds_read_b64_tr_b16 v[218:219], v197 offset:0x3a00
	s_waitcnt lgkmcnt(6)
	v_mfma_f32_32x32x16_bf16 v[48:63], v[204:207], v[144:147], v[48:63]
	ds_read_b64_tr_b16 v[204:205], v197 offset:0x400
	ds_read_b64_tr_b16 v[206:207], v197 offset:0xc00
	s_waitcnt lgkmcnt(6)
	v_mfma_f32_32x32x16_bf16 v[48:63], v[208:211], v[148:151], v[48:63]
	ds_read_b64_tr_b16 v[208:209], v197 offset:0x1400
	ds_read_b64_tr_b16 v[210:211], v197 offset:0x1c00
	s_waitcnt lgkmcnt(6)
	v_mfma_f32_32x32x16_bf16 v[48:63], v[212:215], v[170:173], v[48:63]
	ds_read_b64_tr_b16 v[212:213], v197 offset:0x2400
	ds_read_b64_tr_b16 v[214:215], v197 offset:0x2c00
	s_waitcnt lgkmcnt(6)
	v_mfma_f32_32x32x16_bf16 v[48:63], v[216:219], v[200:203], v[48:63]
	ds_read_b64_tr_b16 v[216:217], v197 offset:0x3400
	ds_read_b64_tr_b16 v[218:219], v197 offset:0x3c00
	s_waitcnt lgkmcnt(6)
	v_mfma_f32_32x32x16_bf16 v[32:47], v[204:207], v[144:147], v[32:47]
	ds_read_b64_tr_b16 v[204:205], v197 offset:0x600
	ds_read_b64_tr_b16 v[206:207], v197 offset:0xe00
	s_waitcnt lgkmcnt(6)
	v_mfma_f32_32x32x16_bf16 v[32:47], v[208:211], v[148:151], v[32:47]
	ds_read_b64_tr_b16 v[208:209], v197 offset:0x1600
	ds_read_b64_tr_b16 v[210:211], v197 offset:0x1e00
	s_waitcnt lgkmcnt(6)
	v_mfma_f32_32x32x16_bf16 v[32:47], v[212:215], v[170:173], v[32:47]
	ds_read_b64_tr_b16 v[212:213], v197 offset:0x2600
	ds_read_b64_tr_b16 v[214:215], v197 offset:0x2e00
	s_waitcnt lgkmcnt(6)
	v_mfma_f32_32x32x16_bf16 v[32:47], v[216:219], v[200:203], v[32:47]
	ds_read_b64_tr_b16 v[216:217], v197 offset:0x3600
	ds_read_b64_tr_b16 v[218:219], v197 offset:0x3e00
	s_waitcnt lgkmcnt(6)
	v_mfma_f32_32x32x16_bf16 v[16:31], v[204:207], v[144:147], v[16:31]
	v_max_f32_e32 v144, v80, v81
	v_max3_f32 v144, v144, v82, v83
	v_max3_f32 v144, v144, v84, v85
	v_max3_f32 v144, v144, v86, v87
	v_max3_f32 v144, v144, v88, v89
	v_max3_f32 v144, v144, v90, v91
	v_max3_f32 v144, v144, v92, v93
	s_waitcnt lgkmcnt(4)
	v_mfma_f32_32x32x16_bf16 v[16:31], v[208:211], v[148:151], v[16:31]
	v_max3_f32 v144, v144, v94, v95
	v_max3_f32 v144, v144, v64, v65
	v_max3_f32 v144, v144, v66, v67
	v_max3_f32 v144, v144, v68, v69
	v_max3_f32 v144, v144, v70, v71
	v_max3_f32 v144, v144, v72, v73
	v_max3_f32 v144, v144, v74, v75
	v_max3_f32 v144, v144, v76, v77
	s_waitcnt lgkmcnt(2)
	v_mfma_f32_32x32x16_bf16 v[16:31], v[212:215], v[170:173], v[16:31]
	v_max3_f32 v144, v144, v78, v79
	v_mov_b32_e32 v145, v144
	s_nop 1
	v_permlane32_swap_b32_e32 v144, v145
	v_max_f32_e32 v144, v144, v145
	v_cmp_ge_f32_e32 vcc, s63, v144
	s_waitcnt lgkmcnt(0)
	v_mfma_f32_32x32x16_bf16 v[16:31], v[216:219], v[200:203], v[16:31]
	s_cmp_eq_u64 vcc, exec
	s_cselect_b64 s[4:5], -1, 0
	s_waitcnt vmcnt(0) lgkmcnt(0)
	s_barrier
	s_cbranch_scc1 .Lal_c_m2
	v_max_f32_e32 v242, 0, v144
	v_exp_f32_e64 v144, -v242
	s_nop 0
	v_pk_mul_f32 v[14:15], v[14:15], v[144:145] op_sel_hi:[1,0]
	v_pk_mul_f32 v[12:13], v[12:13], v[144:145] op_sel_hi:[1,0]
	v_pk_mul_f32 v[10:11], v[10:11], v[144:145] op_sel_hi:[1,0]
	v_pk_mul_f32 v[8:9], v[8:9], v[144:145] op_sel_hi:[1,0]
	v_pk_mul_f32 v[6:7], v[6:7], v[144:145] op_sel_hi:[1,0]
	v_pk_mul_f32 v[4:5], v[4:5], v[144:145] op_sel_hi:[1,0]
	v_pk_mul_f32 v[2:3], v[2:3], v[144:145] op_sel_hi:[1,0]
	v_pk_mul_f32 v[0:1], v[0:1], v[144:145] op_sel_hi:[1,0]
	v_pk_mul_f32 v[62:63], v[62:63], v[144:145] op_sel_hi:[1,0]
	v_pk_mul_f32 v[60:61], v[60:61], v[144:145] op_sel_hi:[1,0]
	v_pk_mul_f32 v[58:59], v[58:59], v[144:145] op_sel_hi:[1,0]
	v_pk_mul_f32 v[56:57], v[56:57], v[144:145] op_sel_hi:[1,0]
	v_pk_mul_f32 v[54:55], v[54:55], v[144:145] op_sel_hi:[1,0]
	v_pk_mul_f32 v[52:53], v[52:53], v[144:145] op_sel_hi:[1,0]
	v_pk_mul_f32 v[50:51], v[50:51], v[144:145] op_sel_hi:[1,0]
	v_pk_mul_f32 v[48:49], v[48:49], v[144:145] op_sel_hi:[1,0]
	v_pk_mul_f32 v[46:47], v[46:47], v[144:145] op_sel_hi:[1,0]
	v_pk_mul_f32 v[44:45], v[44:45], v[144:145] op_sel_hi:[1,0]
	v_pk_mul_f32 v[42:43], v[42:43], v[144:145] op_sel_hi:[1,0]
	v_pk_mul_f32 v[40:41], v[40:41], v[144:145] op_sel_hi:[1,0]
	v_pk_mul_f32 v[38:39], v[38:39], v[144:145] op_sel_hi:[1,0]
	v_pk_mul_f32 v[36:37], v[36:37], v[144:145] op_sel_hi:[1,0]
	v_pk_mul_f32 v[34:35], v[34:35], v[144:145] op_sel_hi:[1,0]
	v_pk_mul_f32 v[32:33], v[32:33], v[144:145] op_sel_hi:[1,0]
	v_pk_mul_f32 v[30:31], v[30:31], v[144:145] op_sel_hi:[1,0]
	v_pk_mul_f32 v[28:29], v[28:29], v[144:145] op_sel_hi:[1,0]
	v_pk_mul_f32 v[26:27], v[26:27], v[144:145] op_sel_hi:[1,0]
	v_pk_mul_f32 v[24:25], v[24:25], v[144:145] op_sel_hi:[1,0]
	v_pk_mul_f32 v[22:23], v[22:23], v[144:145] op_sel_hi:[1,0]
	v_pk_mul_f32 v[20:21], v[20:21], v[144:145] op_sel_hi:[1,0]
	v_pk_mul_f32 v[18:19], v[18:19], v[144:145] op_sel_hi:[1,0]
	v_pk_mul_f32 v[16:17], v[16:17], v[144:145] op_sel_hi:[1,0]
	v_sub_f32_e32 v80, v80, v242
	v_sub_f32_e32 v81, v81, v242
	v_sub_f32_e32 v82, v82, v242
	v_sub_f32_e32 v83, v83, v242
	v_sub_f32_e32 v84, v84, v242
	v_sub_f32_e32 v85, v85, v242
	v_sub_f32_e32 v86, v86, v242
	v_sub_f32_e32 v87, v87, v242
	v_sub_f32_e32 v88, v88, v242
	v_sub_f32_e32 v89, v89, v242
	v_sub_f32_e32 v90, v90, v242
	v_sub_f32_e32 v91, v91, v242
	v_sub_f32_e32 v92, v92, v242
	v_sub_f32_e32 v93, v93, v242
	v_sub_f32_e32 v94, v94, v242
	v_sub_f32_e32 v95, v95, v242
	v_sub_f32_e32 v64, v64, v242
	v_sub_f32_e32 v65, v65, v242
	v_sub_f32_e32 v66, v66, v242
	v_sub_f32_e32 v67, v67, v242
	v_sub_f32_e32 v68, v68, v242
	v_sub_f32_e32 v69, v69, v242
	v_sub_f32_e32 v70, v70, v242
	v_sub_f32_e32 v71, v71, v242
	v_sub_f32_e32 v72, v72, v242
	v_sub_f32_e32 v73, v73, v242
	v_sub_f32_e32 v74, v74, v242
	v_sub_f32_e32 v75, v75, v242
	v_sub_f32_e32 v76, v76, v242
	v_sub_f32_e32 v77, v77, v242
	v_sub_f32_e32 v78, v78, v242
	v_sub_f32_e32 v79, v79, v242
	v_sub_f32_e32 v226, v226, v242
	v_sub_f32_e32 v227, v227, v242
	v_sub_f32_e32 v228, v228, v242
	v_sub_f32_e32 v229, v229, v242
	v_sub_f32_e32 v230, v230, v242
	v_sub_f32_e32 v231, v231, v242
	v_sub_f32_e32 v232, v232, v242
	v_sub_f32_e32 v233, v233, v242
	v_sub_f32_e32 v234, v234, v242
	v_sub_f32_e32 v235, v235, v242
	v_sub_f32_e32 v236, v236, v242
	v_sub_f32_e32 v237, v237, v242
	v_sub_f32_e32 v238, v238, v242
	v_sub_f32_e32 v239, v239, v242
	v_sub_f32_e32 v240, v240, v242
	v_sub_f32_e32 v241, v241, v242
	s_branch .LBB0_119

; __device__ __forceinline__ void finishSM(f32x16& p0, f32x16& p1, float alpha, float& l_reg, bf16x8& pa0, bf16x8& pa1, bf16x8& pa2, bf16x8& pa3) {
; #pragma unroll
;   for (int r = 0; r < 16; ++r) p1[r] = __builtin_amdgcn_exp2f(p1[r]);
;   float ps = 0;
; #pragma unroll
;   for (int r = 0; r < 16; ++r) ps += p0[r];
; #pragma unroll
;   for (int r = 0; r < 16; ++r) ps += p1[r];
;   { auto rr = __builtin_amdgcn_permlane32_swap(__float_as_uint(ps), __float_as_uint(ps), false, false);
;     ps = __uint_as_float(rr[0]) + __uint_as_float(rr[1]); }
;   l_reg = l_reg * alpha + ps;
;     ...
;   PK4(p0, 0, pa0); PK4(p0, 8, pa1); PK4(p1, 0, pa2); PK4(p1, 8, pa3);
;     ...
; }
; template <int BUFOFF>
; __device__ __forceinline__ void qkt_diff(f32x16& p0, f32x16& p1, const int* ka, const bf16x8* qr) {
;   typedef __attribute__((address_space(3))) const bf16x8* lp;
;   p0 = f32x16{}; p1 = f32x16{};
; #pragma unroll
;   for (int d0 = 0; d0 < 4; ++d0) {
;     const int a = ka[d0] + BUFOFF;
;     const bf16x8 b0 = *(lp)(a), b1 = *(lp)(a + 8192);
;     p0 = __builtin_amdgcn_mfma_f32_32x32x16_bf16(b0, qr[d0], p0, 0, 0, 0);
;     p1 = __builtin_amdgcn_mfma_f32_32x32x16_bf16(b1, qr[d0], p1, 0, 0, 0);
;   }
; }
.LBB0_129:
	s_mov_b32 s54, s47
	s_mov_b32 s47, s52
	ds_read_b128 v[64:67], v138 offset:16384
	ds_read_b128 v[68:71], v138 offset:24576
	ds_read_b128 v[170:173], v141 offset:16384
	ds_read_b128 v[188:191], v141 offset:24576
	s_waitcnt lgkmcnt(0)
	v_mfma_f32_32x32x16_bf16 v[80:95], v[64:67], v[108:111], v[226:241]
	v_add_f32_e32 v112, v144, v113
	v_mfma_f32_32x32x16_bf16 v[64:79], v[68:71], v[108:111], v[226:241]
	v_add_f32_e32 v243, v148, v155
	v_add_f32_e32 v244, v145, v152
	v_add_f32_e32 v245, v149, v156
	v_add_f32_e32 v246, v146, v153
	v_add_f32_e32 v247, v150, v158
	v_mfma_f32_32x32x16_bf16 v[80:95], v[170:173], v[104:107], v[80:95]
	v_add_f32_e32 v251, v147, v154
	v_add_f32_e32 v252, v151, v159
	v_mov_b32_e32 v132, v124
	v_add_f32_e32 v112, v128, v112
	v_mov_b32_e32 v162, v125
	v_mfma_f32_32x32x16_bf16 v[64:79], v[188:191], v[104:107], v[64:79]
	ds_read_b128 v[170:173], v140 offset:16384
	ds_read_b128 v[188:191], v140 offset:24576
	v_add_f32_e32 v243, v129, v243
	v_mov_b32_e32 v167, v120
	v_add_f32_e32 v244, v126, v244
	v_mov_b32_e32 v169, v121
	v_add_f32_e32 v245, v127, v245
	v_add_f32_e32 v246, v124, v246
	s_waitcnt lgkmcnt(0)
	v_mfma_f32_32x32x16_bf16 v[80:95], v[170:173], v[100:103], v[80:95]
	v_add_f32_e32 v247, v125, v247
	v_add_f32_e32 v251, v120, v251
	v_add_f32_e32 v252, v121, v252
	v_mfma_f32_32x32x16_bf16 v[64:79], v[188:191], v[100:103], v[64:79]
	ds_read_b128 v[170:173], v139 offset:16384
	ds_read_b128 v[188:191], v139 offset:24576
	s_waitcnt lgkmcnt(0)
	v_mfma_f32_32x32x16_bf16 v[80:95], v[170:173], v[96:99], v[80:95]
	v_mov_b32_e32 v170, v118
	v_mov_b32_e32 v171, v117
	v_mov_b32_e32 v172, v114
	v_mov_b32_e32 v173, v115
	v_add_f32_e32 v112, v118, v112
	v_add_f32_e32 v243, v119, v243
	v_add_f32_e32 v244, v116, v244
	v_mfma_f32_32x32x16_bf16 v[64:79], v[188:191], v[96:99], v[64:79]
	v_mov_b32_e32 v188, v122
	v_mov_b32_e32 v189, v123
	v_add_f32_e32 v245, v117, v245
	v_add_f32_e32 v246, v114, v246
	v_add_f32_e32 v247, v115, v247
	v_add_f32_e32 v251, v122, v251
	v_add_f32_e32 v252, v123, v252
	v_add_f32_e32 v112, v112, v243
	v_add_f32_e32 v244, v244, v245
	v_add_f32_e32 v246, v246, v247
	v_add_f32_e32 v251, v251, v252
	v_add_f32_e32 v112, v112, v244
	v_add_f32_e32 v246, v246, v251
	v_add_f32_e32 v117, v112, v246
	v_mov_b32_e32 v118, v117
	v_cvt_pk_bf16_f32 v112, v113, v155
	v_cvt_pk_bf16_f32 v113, v152, v156
	v_cvt_pk_bf16_f32 v114, v153, v158
	s_nop 1
	v_permlane32_swap_b32_e32 v117, v118
	v_cvt_pk_bf16_f32 v115, v154, v159
	v_cvt_pk_bf16_f32 v120, v144, v148
	v_cvt_pk_bf16_f32 v121, v145, v149
	v_cvt_pk_bf16_f32 v122, v146, v150
	v_cvt_pk_bf16_f32 v123, v147, v151
	v_cvt_pk_bf16_f32 v124, v128, v129
	v_cvt_pk_bf16_f32 v125, v126, v127
	v_cvt_pk_bf16_f32 v126, v132, v162
	v_cvt_pk_bf16_f32 v127, v167, v169
	v_cvt_pk_bf16_f32 v144, v170, v119
	v_cvt_pk_bf16_f32 v145, v116, v171
	v_cvt_pk_bf16_f32 v146, v172, v173
	v_cvt_pk_bf16_f32 v147, v188, v189
	s_add_u32 s4, s14, 0x2000000
	s_mov_b32 m0, s43
	s_addc_u32 s5, s15, 0
	s_mov_b64 s[56:57], s[14:15]
	s_lshl_b32 s52, s53, 14
	s_add_i32 s55, s42, s52
	s_nop 0
	global_load_lds_dwordx4 v134, s[56:57]
	s_mov_b32 m0, s44
	s_nop 0
	global_load_lds_dwordx4 v135, s[56:57]
	s_mov_b32 m0, s55
	s_nop 0
	global_load_lds_dwordx4 v136, s[4:5]
	s_add_i32 m0, s55, 0x2000
	s_nop 0
	global_load_lds_dwordx4 v137, s[4:5]
	s_lshl_b32 s55, s47, 14
	v_add_u32_e32 v132, s55, v133
	ds_read_b64_tr_b16 v[148:149], v132 offset:0
	ds_read_b64_tr_b16 v[150:151], v132 offset:0x800
	ds_read_b64_tr_b16 v[152:153], v132 offset:0x1000
	ds_read_b64_tr_b16 v[154:155], v132 offset:0x1800
	ds_read_b64_tr_b16 v[170:171], v132 offset:0x2000
	ds_read_b64_tr_b16 v[172:173], v132 offset:0x2800
	ds_read_b64_tr_b16 v[188:189], v132 offset:0x3000
	ds_read_b64_tr_b16 v[190:191], v132 offset:0x3800
	s_nop 0
	s_waitcnt lgkmcnt(6)
	v_mfma_f32_32x32x16_bf16 v[32:47], v[148:151], v[112:115], v[32:47]
	ds_read_b64_tr_b16 v[148:149], v132 offset:0x200
	ds_read_b64_tr_b16 v[150:151], v132 offset:0xa00
	s_waitcnt lgkmcnt(6)
	v_mfma_f32_32x32x16_bf16 v[32:47], v[152:155], v[120:123], v[32:47]
	ds_read_b64_tr_b16 v[152:153], v132 offset:0x1200
	ds_read_b64_tr_b16 v[154:155], v132 offset:0x1a00
	s_waitcnt lgkmcnt(6)
	v_mfma_f32_32x32x16_bf16 v[32:47], v[170:173], v[124:127], v[32:47]
	ds_read_b64_tr_b16 v[170:171], v132 offset:0x2200
	ds_read_b64_tr_b16 v[172:173], v132 offset:0x2a00
	s_waitcnt lgkmcnt(6)
	v_mfma_f32_32x32x16_bf16 v[32:47], v[188:191], v[144:147], v[32:47]
	ds_read_b64_tr_b16 v[188:189], v132 offset:0x3200
	ds_read_b64_tr_b16 v[190:191], v132 offset:0x3a00
	s_waitcnt lgkmcnt(6)
	v_mfma_f32_32x32x16_bf16 v[48:63], v[148:151], v[112:115], v[48:63]
	ds_read_b64_tr_b16 v[148:149], v132 offset:0x400
	ds_read_b64_tr_b16 v[150:151], v132 offset:0xc00
	s_waitcnt lgkmcnt(6)
	v_mfma_f32_32x32x16_bf16 v[48:63], v[152:155], v[120:123], v[48:63]
	ds_read_b64_tr_b16 v[152:153], v132 offset:0x1400
	ds_read_b64_tr_b16 v[154:155], v132 offset:0x1c00
	s_waitcnt lgkmcnt(6)
	v_mfma_f32_32x32x16_bf16 v[48:63], v[170:173], v[124:127], v[48:63]
	ds_read_b64_tr_b16 v[170:171], v132 offset:0x2400
	ds_read_b64_tr_b16 v[172:173], v132 offset:0x2c00
	s_waitcnt lgkmcnt(6)
	v_mfma_f32_32x32x16_bf16 v[48:63], v[188:191], v[144:147], v[48:63]
	ds_read_b64_tr_b16 v[188:189], v132 offset:0x3400
	ds_read_b64_tr_b16 v[190:191], v132 offset:0x3c00
	s_waitcnt lgkmcnt(6)
; #define SBAR() __builtin_amdgcn_sched_barrier(0)
; template <int MLA>
; __device__ __forceinline__ void partialSM(f32x16& p0, f32x16& p1, float& m_reg, float& mn, float& alpha) {
;   constexpr float SCALE = AttC<MLA>::SCALE;
;   constexpr float C = SCALE * 1.4426950408889634f;
;   float pmax = p0[0];
; #pragma unroll
;   for (int r = 1; r < 16; ++r) pmax = fmaxf(pmax, p0[r]);
; #pragma unroll
;   for (int r = 0; r < 16; ++r) pmax = fmaxf(pmax, p1[r]);
;   { auto rr = __builtin_amdgcn_permlane32_swap(__float_as_uint(pmax), __float_as_uint(pmax), false, false);
;     pmax = fmaxf(__uint_as_float(rr[0]), __uint_as_float(rr[1])); }
;   if (__builtin_expect(__all(pmax - m_reg <= THR / SCALE), 1)) { mn = m_reg; alpha = 1.f; }
;   else { mn = fmaxf(m_reg, pmax); alpha = __builtin_amdgcn_exp2f((m_reg - mn) * C); m_reg = mn; }
;   float mnC = -mn * C;
; #pragma unroll
;   for (int r = 0; r < 16; ++r) p0[r] = fmaf(p0[r], C, mnC);
; #pragma unroll
;   for (int r = 0; r < 16; ++r) p1[r] = fmaf(p1[r], C, mnC);
; #pragma unroll
;   for (int r = 0; r < 16; ++r) p0[r] = __builtin_amdgcn_exp2f(p0[r]);
; }
; template <int D0> __device__ __forceinline__ void pv_one_t(f32x16& od, int vb, bf16x8 pa0, bf16x8 pa1, bf16x8 pa2, bf16x8 pa3) {
;   const s16x4 l0 = tr_read<v_rd_off(D0, 0, 0)>(vb), h0 = tr_read<v_rd_off(D0, 0, 1)>(vb), l1 = tr_read<v_rd_off(D0, 1, 0)>(vb), h1 = tr_read<v_rd_off(D0, 1, 1)>(vb);
;   const s16x4 l2 = tr_read<v_rd_off(D0, 2, 0)>(vb), h2 = tr_read<v_rd_off(D0, 2, 1)>(vb), l3 = tr_read<v_rd_off(D0, 3, 0)>(vb), h3 = tr_read<v_rd_off(D0, 3, 1)>(vb);
;   asm volatile("s_waitcnt lgkmcnt(0)" ::: "memory"); SBAR();
;     ...
;   od = __builtin_amdgcn_mfma_f32_32x32x16_bf16(PK(l0, h0), pa0, od, 0, 0, 0);
;   od = __builtin_amdgcn_mfma_f32_32x32x16_bf16(PK(l1, h1), pa1, od, 0, 0, 0);
;   od = __builtin_amdgcn_mfma_f32_32x32x16_bf16(PK(l2, h2), pa2, od, 0, 0, 0);
;   od = __builtin_amdgcn_mfma_f32_32x32x16_bf16(PK(l3, h3), pa3, od, 0, 0, 0);
;     ...
; }
; __device__ __forceinline__ void pv_d0_t(f32x16* o, int vb, bf16x8 pa0, bf16x8 pa1, bf16x8 pa2, bf16x8 pa3) {
;   pv_one_t<0>(o[0], vb, pa0, pa1, pa2, pa3); pv_one_t<1>(o[1], vb, pa0, pa1, pa2, pa3); pv_one_t<2>(o[2], vb, pa0, pa1, pa2, pa3); pv_one_t<3>(o[3], vb, pa0, pa1, pa2, pa3);
; }
	v_mfma_f32_32x32x16_bf16 v[16:31], v[148:151], v[112:115], v[16:31]
	ds_read_b64_tr_b16 v[148:149], v132 offset:0x600
	ds_read_b64_tr_b16 v[150:151], v132 offset:0xe00
	s_waitcnt lgkmcnt(6)
	v_mfma_f32_32x32x16_bf16 v[16:31], v[152:155], v[120:123], v[16:31]
	ds_read_b64_tr_b16 v[152:153], v132 offset:0x1600
	ds_read_b64_tr_b16 v[154:155], v132 offset:0x1e00
	s_waitcnt lgkmcnt(6)
	v_mfma_f32_32x32x16_bf16 v[16:31], v[170:173], v[124:127], v[16:31]
	ds_read_b64_tr_b16 v[170:171], v132 offset:0x2600
	ds_read_b64_tr_b16 v[172:173], v132 offset:0x2e00
	s_waitcnt lgkmcnt(6)
	v_mfma_f32_32x32x16_bf16 v[16:31], v[188:191], v[144:147], v[16:31]
	ds_read_b64_tr_b16 v[188:189], v132 offset:0x3600
	ds_read_b64_tr_b16 v[190:191], v132 offset:0x3e00
	s_waitcnt lgkmcnt(6)
	v_mfma_f32_32x32x16_bf16 v[0:15], v[148:151], v[112:115], v[0:15]
	v_max_f32_e32 v112, v80, v81
	v_max3_f32 v112, v112, v82, v83
	v_max3_f32 v112, v112, v84, v85
	v_max3_f32 v112, v112, v86, v87
	v_max3_f32 v112, v112, v88, v89
	v_max3_f32 v112, v112, v90, v91
	v_max3_f32 v112, v112, v92, v93
	s_waitcnt lgkmcnt(4)
	v_mfma_f32_32x32x16_bf16 v[0:15], v[152:155], v[120:123], v[0:15]
	v_max3_f32 v112, v112, v94, v95
	v_max3_f32 v112, v112, v64, v65
	v_max3_f32 v112, v112, v66, v67
	v_max3_f32 v112, v112, v68, v69
	v_max3_f32 v112, v112, v70, v71
	v_max3_f32 v112, v112, v72, v73
	v_max3_f32 v112, v112, v74, v75
	v_max3_f32 v112, v112, v76, v77
	s_waitcnt lgkmcnt(2)
	v_mfma_f32_32x32x16_bf16 v[0:15], v[170:173], v[124:127], v[0:15]
	v_max3_f32 v112, v112, v78, v79
	v_mov_b32_e32 v113, v112
	s_nop 1
	v_permlane32_swap_b32_e32 v112, v113
	v_max_f32_e32 v112, v112, v113
	v_cmp_ge_f32_e32 vcc, s70, v112
	s_waitcnt lgkmcnt(0)
	v_mfma_f32_32x32x16_bf16 v[0:15], v[188:191], v[144:147], v[0:15]
	s_cmp_eq_u64 vcc, exec
	s_cselect_b64 s[4:5], -1, 0
	s_waitcnt vmcnt(0) lgkmcnt(0)
	s_barrier
	s_cbranch_scc1 .Lal_c_d1
	v_max_f32_e32 v242, 0, v112
	v_exp_f32_e64 v116, -v242
	s_nop 0
	v_pk_mul_f32 v[46:47], v[46:47], v[116:117] op_sel_hi:[1,0]
	v_pk_mul_f32 v[44:45], v[44:45], v[116:117] op_sel_hi:[1,0]
	v_pk_mul_f32 v[42:43], v[42:43], v[116:117] op_sel_hi:[1,0]
	v_pk_mul_f32 v[40:41], v[40:41], v[116:117] op_sel_hi:[1,0]
	v_pk_mul_f32 v[38:39], v[38:39], v[116:117] op_sel_hi:[1,0]
	v_pk_mul_f32 v[36:37], v[36:37], v[116:117] op_sel_hi:[1,0]
	v_pk_mul_f32 v[34:35], v[34:35], v[116:117] op_sel_hi:[1,0]
	v_pk_mul_f32 v[32:33], v[32:33], v[116:117] op_sel_hi:[1,0]
	v_pk_mul_f32 v[62:63], v[62:63], v[116:117] op_sel_hi:[1,0]
	v_pk_mul_f32 v[60:61], v[60:61], v[116:117] op_sel_hi:[1,0]
	v_pk_mul_f32 v[58:59], v[58:59], v[116:117] op_sel_hi:[1,0]
	v_pk_mul_f32 v[56:57], v[56:57], v[116:117] op_sel_hi:[1,0]
	v_pk_mul_f32 v[54:55], v[54:55], v[116:117] op_sel_hi:[1,0]
	v_pk_mul_f32 v[52:53], v[52:53], v[116:117] op_sel_hi:[1,0]
	v_pk_mul_f32 v[50:51], v[50:51], v[116:117] op_sel_hi:[1,0]
	v_pk_mul_f32 v[48:49], v[48:49], v[116:117] op_sel_hi:[1,0]
	v_pk_mul_f32 v[30:31], v[30:31], v[116:117] op_sel_hi:[1,0]
	v_pk_mul_f32 v[28:29], v[28:29], v[116:117] op_sel_hi:[1,0]
	v_pk_mul_f32 v[26:27], v[26:27], v[116:117] op_sel_hi:[1,0]
	v_pk_mul_f32 v[24:25], v[24:25], v[116:117] op_sel_hi:[1,0]
	v_pk_mul_f32 v[22:23], v[22:23], v[116:117] op_sel_hi:[1,0]
	v_pk_mul_f32 v[20:21], v[20:21], v[116:117] op_sel_hi:[1,0]
	v_pk_mul_f32 v[18:19], v[18:19], v[116:117] op_sel_hi:[1,0]
	v_pk_mul_f32 v[16:17], v[16:17], v[116:117] op_sel_hi:[1,0]
	v_pk_mul_f32 v[14:15], v[14:15], v[116:117] op_sel_hi:[1,0]
	v_pk_mul_f32 v[12:13], v[12:13], v[116:117] op_sel_hi:[1,0]
	v_pk_mul_f32 v[10:11], v[10:11], v[116:117] op_sel_hi:[1,0]
	v_pk_mul_f32 v[8:9], v[8:9], v[116:117] op_sel_hi:[1,0]
	v_pk_mul_f32 v[6:7], v[6:7], v[116:117] op_sel_hi:[1,0]
	v_pk_mul_f32 v[4:5], v[4:5], v[116:117] op_sel_hi:[1,0]
	v_pk_mul_f32 v[2:3], v[2:3], v[116:117] op_sel_hi:[1,0]
	v_pk_mul_f32 v[0:1], v[0:1], v[116:117] op_sel_hi:[1,0]
	v_sub_f32_e32 v80, v80, v242
	v_sub_f32_e32 v81, v81, v242
	v_sub_f32_e32 v82, v82, v242
	v_sub_f32_e32 v83, v83, v242
	v_sub_f32_e32 v84, v84, v242
	v_sub_f32_e32 v85, v85, v242
	v_sub_f32_e32 v86, v86, v242
	v_sub_f32_e32 v87, v87, v242
	v_sub_f32_e32 v88, v88, v242
	v_sub_f32_e32 v89, v89, v242
	v_sub_f32_e32 v90, v90, v242
	v_sub_f32_e32 v91, v91, v242
	v_sub_f32_e32 v92, v92, v242
	v_sub_f32_e32 v93, v93, v242
	v_sub_f32_e32 v94, v94, v242
	v_sub_f32_e32 v95, v95, v242
	v_sub_f32_e32 v64, v64, v242
	v_sub_f32_e32 v65, v65, v242
	v_sub_f32_e32 v66, v66, v242
	v_sub_f32_e32 v67, v67, v242
	v_sub_f32_e32 v68, v68, v242
	v_sub_f32_e32 v69, v69, v242
	v_sub_f32_e32 v70, v70, v242
	v_sub_f32_e32 v71, v71, v242
	v_sub_f32_e32 v72, v72, v242
	v_sub_f32_e32 v73, v73, v242
	v_sub_f32_e32 v74, v74, v242
	v_sub_f32_e32 v75, v75, v242
	v_sub_f32_e32 v76, v76, v242
	v_sub_f32_e32 v77, v77, v242
	v_sub_f32_e32 v78, v78, v242
	v_sub_f32_e32 v79, v79, v242
	v_sub_f32_e32 v226, v226, v242
	v_sub_f32_e32 v227, v227, v242
	v_sub_f32_e32 v228, v228, v242
	v_sub_f32_e32 v229, v229, v242
	v_sub_f32_e32 v230, v230, v242
	v_sub_f32_e32 v231, v231, v242
	v_sub_f32_e32 v232, v232, v242
	v_sub_f32_e32 v233, v233, v242
	v_sub_f32_e32 v234, v234, v242
	v_sub_f32_e32 v235, v235, v242
	v_sub_f32_e32 v236, v236, v242
	v_sub_f32_e32 v237, v237, v242
	v_sub_f32_e32 v238, v238, v242
	v_sub_f32_e32 v239, v239, v242
	v_sub_f32_e32 v240, v240, v242
	v_sub_f32_e32 v241, v241, v242
	s_branch .LBB0_131

; __device__ __forceinline__ void finishSM(f32x16& p0, f32x16& p1, float alpha, float& l_reg, bf16x8& pa0, bf16x8& pa1, bf16x8& pa2, bf16x8& pa3) {
; #pragma unroll
;   for (int r = 0; r < 16; ++r) p1[r] = __builtin_amdgcn_exp2f(p1[r]);
;   float ps = 0;
; #pragma unroll
;   for (int r = 0; r < 16; ++r) ps += p0[r];
; #pragma unroll
;   for (int r = 0; r < 16; ++r) ps += p1[r];
;   { auto rr = __builtin_amdgcn_permlane32_swap(__float_as_uint(ps), __float_as_uint(ps), false, false);
;     ps = __uint_as_float(rr[0]) + __uint_as_float(rr[1]); }
;   l_reg = l_reg * alpha + ps;
;     ...
;   PK4(p0, 0, pa0); PK4(p0, 8, pa1); PK4(p1, 0, pa2); PK4(p1, 8, pa3);
;     ...
; }
; template <int BUFOFF>
; __device__ __forceinline__ void qkt_diff(f32x16& p0, f32x16& p1, const int* ka, const bf16x8* qr) {
;   typedef __attribute__((address_space(3))) const bf16x8* lp;
;   p0 = f32x16{}; p1 = f32x16{};
; #pragma unroll
;   for (int d0 = 0; d0 < 4; ++d0) {
;     const int a = ka[d0] + BUFOFF;
;     const bf16x8 b0 = *(lp)(a), b1 = *(lp)(a + 8192);
;     p0 = __builtin_amdgcn_mfma_f32_32x32x16_bf16(b0, qr[d0], p0, 0, 0, 0);
;     p1 = __builtin_amdgcn_mfma_f32_32x32x16_bf16(b1, qr[d0], p1, 0, 0, 0);
;   }
; }
.LBB0_131:
	v_exp_f32_e32 v125, v64
	v_exp_f32_e32 v126, v65
	v_exp_f32_e32 v127, v66
	v_exp_f32_e32 v128, v67
	v_exp_f32_e32 v129, v68
	v_exp_f32_e32 v143, v69
	v_exp_f32_e32 v144, v70
	v_exp_f32_e32 v145, v71
	v_exp_f32_e32 v146, v72
	v_exp_f32_e32 v147, v73
	v_exp_f32_e32 v148, v74
	v_exp_f32_e32 v149, v75
	v_exp_f32_e32 v150, v76
	v_exp_f32_e32 v151, v80
	v_exp_f32_e32 v152, v81
	v_exp_f32_e32 v153, v82
	v_exp_f32_e32 v154, v83
	v_exp_f32_e32 v155, v84
	v_exp_f32_e32 v156, v85
	v_exp_f32_e32 v158, v86
	v_exp_f32_e32 v159, v87
	v_exp_f32_e32 v162, v88
	v_exp_f32_e32 v167, v89
	v_exp_f32_e32 v169, v90
	v_exp_f32_e32 v170, v91
	v_exp_f32_e32 v171, v92
	v_exp_f32_e32 v172, v93
	v_exp_f32_e32 v173, v94
	v_exp_f32_e32 v188, v95
	v_exp_f32_e32 v189, v77
	v_exp_f32_e32 v190, v78
	v_exp_f32_e32 v124, v79
	ds_read_b128 v[64:67], v138
	ds_read_b128 v[68:71], v138 offset:8192
	ds_read_b128 v[112:115], v141
	ds_read_b128 v[120:123], v141 offset:8192
	v_mov_b32_e32 v191, v125
	s_waitcnt lgkmcnt(0)
	v_mfma_f32_32x32x16_bf16 v[80:95], v[64:67], v[108:111], v[226:241]
	v_mfma_f32_32x32x16_bf16 v[64:79], v[68:71], v[108:111], v[226:241]
	v_mov_b32_e32 v192, v124
	v_mfma_f32_32x32x16_bf16 v[80:95], v[112:115], v[104:107], v[80:95]
	v_mfma_f32_32x32x16_bf16 v[64:79], v[120:123], v[104:107], v[64:79]
	ds_read_b128 v[112:115], v140
	ds_read_b128 v[120:123], v140 offset:8192
	s_waitcnt lgkmcnt(0)
	v_mfma_f32_32x32x16_bf16 v[80:95], v[112:115], v[100:103], v[80:95]
	v_mfma_f32_32x32x16_bf16 v[64:79], v[120:123], v[100:103], v[64:79]
	ds_read_b128 v[112:115], v139
	ds_read_b128 v[120:123], v139 offset:8192
	s_waitcnt lgkmcnt(0)
	v_mfma_f32_32x32x16_bf16 v[80:95], v[112:115], v[96:99], v[80:95]
	v_add_f32_e32 v112, v162, v151
	v_add_f32_e32 v243, v167, v152
	v_add_f32_e32 v244, v169, v153
	v_add_f32_e32 v245, v170, v154
	v_add_f32_e32 v246, v171, v155
	v_add_f32_e32 v247, v172, v156
	v_add_f32_e32 v251, v173, v158
	v_add_f32_e32 v252, v188, v159
	v_add_f32_e32 v112, v125, v112
	v_add_f32_e32 v243, v126, v243
	v_add_f32_e32 v244, v127, v244
	v_add_f32_e32 v245, v128, v245
	v_add_f32_e32 v246, v129, v246
	v_add_f32_e32 v247, v143, v247
	v_add_f32_e32 v251, v144, v251
	v_add_f32_e32 v252, v145, v252
	v_add_f32_e32 v112, v146, v112
	v_add_f32_e32 v243, v147, v243
	v_mfma_f32_32x32x16_bf16 v[64:79], v[120:123], v[96:99], v[64:79]
	v_add_f32_e32 v244, v148, v244
	v_add_f32_e32 v245, v149, v245
	v_add_f32_e32 v246, v150, v246
	v_add_f32_e32 v247, v189, v247
	v_add_f32_e32 v251, v190, v251
	v_add_f32_e32 v252, v124, v252
	v_add_f32_e32 v112, v112, v243
	v_add_f32_e32 v244, v244, v245
	v_add_f32_e32 v246, v246, v247
	v_add_f32_e32 v251, v251, v252
	v_add_f32_e32 v112, v112, v244
	v_add_f32_e32 v246, v246, v251
	v_add_f32_e32 v120, v112, v246
	v_mov_b32_e32 v121, v120
	v_cvt_pk_bf16_f32 v112, v151, v152
	v_cvt_pk_bf16_f32 v113, v153, v154
	v_cvt_pk_bf16_f32 v114, v155, v156
	v_cvt_pk_bf16_f32 v115, v158, v159
	s_nop 1
	v_permlane32_swap_b32_e32 v120, v121
	v_cvt_pk_bf16_f32 v122, v162, v167
	v_cvt_pk_bf16_f32 v123, v169, v170
	v_cvt_pk_bf16_f32 v124, v171, v172
	v_cvt_pk_bf16_f32 v125, v173, v188
	v_cvt_pk_bf16_f32 v126, v191, v126
	v_cvt_pk_bf16_f32 v127, v127, v128
	v_cvt_pk_bf16_f32 v128, v129, v143
	v_cvt_pk_bf16_f32 v129, v144, v145
	v_cvt_pk_bf16_f32 v144, v146, v147
	v_cvt_pk_bf16_f32 v145, v148, v149
	v_cvt_pk_bf16_f32 v146, v150, v189
	v_cvt_pk_bf16_f32 v147, v190, v192
	s_nop 0
	s_add_u32 s4, s14, 0x20000
	s_addc_u32 s5, s15, 0
	s_add_u32 s56, s14, 0x2020000
	s_mov_b32 m0, s16
	s_addc_u32 s57, s15, 0
	s_add_i32 s55, s42, s55
	s_nop 0
	global_load_lds_dwordx4 v134, s[4:5]
	s_mov_b32 m0, s17
	s_nop 0
	global_load_lds_dwordx4 v135, s[4:5]
	s_mov_b32 m0, s55
	s_nop 0
	global_load_lds_dwordx4 v136, s[56:57]
	s_add_i32 m0, s55, 0x2000
	s_nop 0
	global_load_lds_dwordx4 v137, s[56:57]
	v_lshl_add_u32 v143, s54, 14, v133
	ds_read_b64_tr_b16 v[148:149], v143 offset:0
	ds_read_b64_tr_b16 v[150:151], v143 offset:0x800
	ds_read_b64_tr_b16 v[152:153], v143 offset:0x1000
	ds_read_b64_tr_b16 v[154:155], v143 offset:0x1800
	ds_read_b64_tr_b16 v[170:171], v143 offset:0x2000
	ds_read_b64_tr_b16 v[172:173], v143 offset:0x2800
	ds_read_b64_tr_b16 v[188:189], v143 offset:0x3000
	ds_read_b64_tr_b16 v[190:191], v143 offset:0x3800
	s_nop 0
	s_waitcnt lgkmcnt(6)
	v_mfma_f32_32x32x16_bf16 v[32:47], v[148:151], v[112:115], v[32:47]
	ds_read_b64_tr_b16 v[148:149], v143 offset:0x200
	ds_read_b64_tr_b16 v[150:151], v143 offset:0xa00
	s_waitcnt lgkmcnt(6)
	v_mfma_f32_32x32x16_bf16 v[32:47], v[152:155], v[122:125], v[32:47]
	ds_read_b64_tr_b16 v[152:153], v143 offset:0x1200
	ds_read_b64_tr_b16 v[154:155], v143 offset:0x1a00
	s_waitcnt lgkmcnt(6)
	v_mfma_f32_32x32x16_bf16 v[32:47], v[170:173], v[126:129], v[32:47]
	ds_read_b64_tr_b16 v[170:171], v143 offset:0x2200
	ds_read_b64_tr_b16 v[172:173], v143 offset:0x2a00
	s_waitcnt lgkmcnt(6)
	v_mfma_f32_32x32x16_bf16 v[32:47], v[188:191], v[144:147], v[32:47]
	ds_read_b64_tr_b16 v[188:189], v143 offset:0x3200
	ds_read_b64_tr_b16 v[190:191], v143 offset:0x3a00
	s_waitcnt lgkmcnt(6)
	v_mfma_f32_32x32x16_bf16 v[48:63], v[148:151], v[112:115], v[48:63]
	ds_read_b64_tr_b16 v[148:149], v143 offset:0x400
	ds_read_b64_tr_b16 v[150:151], v143 offset:0xc00
	s_waitcnt lgkmcnt(6)
	v_mfma_f32_32x32x16_bf16 v[48:63], v[152:155], v[122:125], v[48:63]
	ds_read_b64_tr_b16 v[152:153], v143 offset:0x1400
	ds_read_b64_tr_b16 v[154:155], v143 offset:0x1c00
	s_waitcnt lgkmcnt(6)
	v_mfma_f32_32x32x16_bf16 v[48:63], v[170:173], v[126:129], v[48:63]
	ds_read_b64_tr_b16 v[170:171], v143 offset:0x2400
	ds_read_b64_tr_b16 v[172:173], v143 offset:0x2c00
	s_waitcnt lgkmcnt(6)
; #define SBAR() __builtin_amdgcn_sched_barrier(0)
; template <int MLA>
; __device__ __forceinline__ void partialSM(f32x16& p0, f32x16& p1, float& m_reg, float& mn, float& alpha) {
;   constexpr float SCALE = AttC<MLA>::SCALE;
;   constexpr float C = SCALE * 1.4426950408889634f;
;   float pmax = p0[0];
; #pragma unroll
;   for (int r = 1; r < 16; ++r) pmax = fmaxf(pmax, p0[r]);
; #pragma unroll
;   for (int r = 0; r < 16; ++r) pmax = fmaxf(pmax, p1[r]);
;   { auto rr = __builtin_amdgcn_permlane32_swap(__float_as_uint(pmax), __float_as_uint(pmax), false, false);
;     pmax = fmaxf(__uint_as_float(rr[0]), __uint_as_float(rr[1])); }
;   if (__builtin_expect(__all(pmax - m_reg <= THR / SCALE), 1)) { mn = m_reg; alpha = 1.f; }
;   else { mn = fmaxf(m_reg, pmax); alpha = __builtin_amdgcn_exp2f((m_reg - mn) * C); m_reg = mn; }
;   float mnC = -mn * C;
; #pragma unroll
;   for (int r = 0; r < 16; ++r) p0[r] = fmaf(p0[r], C, mnC);
; #pragma unroll
;   for (int r = 0; r < 16; ++r) p1[r] = fmaf(p1[r], C, mnC);
; #pragma unroll
;   for (int r = 0; r < 16; ++r) p0[r] = __builtin_amdgcn_exp2f(p0[r]);
; }
; template <int D0> __device__ __forceinline__ void pv_one_t(f32x16& od, int vb, bf16x8 pa0, bf16x8 pa1, bf16x8 pa2, bf16x8 pa3) {
;   const s16x4 l0 = tr_read<v_rd_off(D0, 0, 0)>(vb), h0 = tr_read<v_rd_off(D0, 0, 1)>(vb), l1 = tr_read<v_rd_off(D0, 1, 0)>(vb), h1 = tr_read<v_rd_off(D0, 1, 1)>(vb);
;   const s16x4 l2 = tr_read<v_rd_off(D0, 2, 0)>(vb), h2 = tr_read<v_rd_off(D0, 2, 1)>(vb), l3 = tr_read<v_rd_off(D0, 3, 0)>(vb), h3 = tr_read<v_rd_off(D0, 3, 1)>(vb);
;   asm volatile("s_waitcnt lgkmcnt(0)" ::: "memory"); SBAR();
;     ...
;   od = __builtin_amdgcn_mfma_f32_32x32x16_bf16(PK(l0, h0), pa0, od, 0, 0, 0);
;   od = __builtin_amdgcn_mfma_f32_32x32x16_bf16(PK(l1, h1), pa1, od, 0, 0, 0);
;   od = __builtin_amdgcn_mfma_f32_32x32x16_bf16(PK(l2, h2), pa2, od, 0, 0, 0);
;   od = __builtin_amdgcn_mfma_f32_32x32x16_bf16(PK(l3, h3), pa3, od, 0, 0, 0);
;     ...
; }
; __device__ __forceinline__ void pv_d0_t(f32x16* o, int vb, bf16x8 pa0, bf16x8 pa1, bf16x8 pa2, bf16x8 pa3) {
;   pv_one_t<0>(o[0], vb, pa0, pa1, pa2, pa3); pv_one_t<1>(o[1], vb, pa0, pa1, pa2, pa3); pv_one_t<2>(o[2], vb, pa0, pa1, pa2, pa3); pv_one_t<3>(o[3], vb, pa0, pa1, pa2, pa3);
; }
	v_mfma_f32_32x32x16_bf16 v[48:63], v[188:191], v[144:147], v[48:63]
	ds_read_b64_tr_b16 v[188:189], v143 offset:0x3400
	ds_read_b64_tr_b16 v[190:191], v143 offset:0x3c00
	s_waitcnt lgkmcnt(6)
	v_mfma_f32_32x32x16_bf16 v[16:31], v[148:151], v[112:115], v[16:31]
	ds_read_b64_tr_b16 v[148:149], v143 offset:0x600
	ds_read_b64_tr_b16 v[150:151], v143 offset:0xe00
	s_waitcnt lgkmcnt(6)
	v_mfma_f32_32x32x16_bf16 v[16:31], v[152:155], v[122:125], v[16:31]
	ds_read_b64_tr_b16 v[152:153], v143 offset:0x1600
	ds_read_b64_tr_b16 v[154:155], v143 offset:0x1e00
	s_waitcnt lgkmcnt(6)
	v_mfma_f32_32x32x16_bf16 v[16:31], v[170:173], v[126:129], v[16:31]
	ds_read_b64_tr_b16 v[170:171], v143 offset:0x2600
	ds_read_b64_tr_b16 v[172:173], v143 offset:0x2e00
	s_waitcnt lgkmcnt(6)
	v_mfma_f32_32x32x16_bf16 v[16:31], v[188:191], v[144:147], v[16:31]
	ds_read_b64_tr_b16 v[188:189], v143 offset:0x3600
	ds_read_b64_tr_b16 v[190:191], v143 offset:0x3e00
	s_waitcnt lgkmcnt(6)
	v_mfma_f32_32x32x16_bf16 v[0:15], v[148:151], v[112:115], v[0:15]
	v_max_f32_e32 v112, v80, v81
	v_max3_f32 v112, v112, v82, v83
	v_max3_f32 v112, v112, v84, v85
	v_max3_f32 v112, v112, v86, v87
	v_max3_f32 v112, v112, v88, v89
	v_max3_f32 v112, v112, v90, v91
	v_max3_f32 v112, v112, v92, v93
	s_waitcnt lgkmcnt(4)
	v_mfma_f32_32x32x16_bf16 v[0:15], v[152:155], v[122:125], v[0:15]
	v_max3_f32 v112, v112, v94, v95
	v_max3_f32 v112, v112, v64, v65
	v_max3_f32 v112, v112, v66, v67
	v_max3_f32 v112, v112, v68, v69
	v_max3_f32 v112, v112, v70, v71
	v_max3_f32 v112, v112, v72, v73
	v_max3_f32 v112, v112, v74, v75
	v_max3_f32 v112, v112, v76, v77
	s_waitcnt lgkmcnt(2)
	v_mfma_f32_32x32x16_bf16 v[0:15], v[170:173], v[126:129], v[0:15]
	v_max3_f32 v112, v112, v78, v79
	v_mov_b32_e32 v113, v112
	s_nop 1
	v_permlane32_swap_b32_e32 v112, v113
	v_max_f32_e32 v112, v112, v113
	v_cmp_ge_f32_e32 vcc, s70, v112
	s_waitcnt lgkmcnt(0)
	v_mfma_f32_32x32x16_bf16 v[0:15], v[188:191], v[144:147], v[0:15]
	s_cmp_eq_u64 vcc, exec
	s_cselect_b64 s[4:5], -1, 0
	s_waitcnt vmcnt(0) lgkmcnt(0)
	s_barrier
	s_cbranch_scc1 .Lal_c_d2
	v_max_f32_e32 v242, 0, v112
	v_exp_f32_e64 v112, -v242
	s_nop 0
	v_pk_mul_f32 v[46:47], v[46:47], v[112:113] op_sel_hi:[1,0]
	v_pk_mul_f32 v[44:45], v[44:45], v[112:113] op_sel_hi:[1,0]
	v_pk_mul_f32 v[42:43], v[42:43], v[112:113] op_sel_hi:[1,0]
	v_pk_mul_f32 v[40:41], v[40:41], v[112:113] op_sel_hi:[1,0]
	v_pk_mul_f32 v[38:39], v[38:39], v[112:113] op_sel_hi:[1,0]
	v_pk_mul_f32 v[36:37], v[36:37], v[112:113] op_sel_hi:[1,0]
	v_pk_mul_f32 v[34:35], v[34:35], v[112:113] op_sel_hi:[1,0]
	v_pk_mul_f32 v[32:33], v[32:33], v[112:113] op_sel_hi:[1,0]
	v_pk_mul_f32 v[62:63], v[62:63], v[112:113] op_sel_hi:[1,0]
	v_pk_mul_f32 v[60:61], v[60:61], v[112:113] op_sel_hi:[1,0]
	v_pk_mul_f32 v[58:59], v[58:59], v[112:113] op_sel_hi:[1,0]
	v_pk_mul_f32 v[56:57], v[56:57], v[112:113] op_sel_hi:[1,0]
	v_pk_mul_f32 v[54:55], v[54:55], v[112:113] op_sel_hi:[1,0]
	v_pk_mul_f32 v[52:53], v[52:53], v[112:113] op_sel_hi:[1,0]
	v_pk_mul_f32 v[50:51], v[50:51], v[112:113] op_sel_hi:[1,0]
	v_pk_mul_f32 v[48:49], v[48:49], v[112:113] op_sel_hi:[1,0]
	v_pk_mul_f32 v[30:31], v[30:31], v[112:113] op_sel_hi:[1,0]
	v_pk_mul_f32 v[28:29], v[28:29], v[112:113] op_sel_hi:[1,0]
	v_pk_mul_f32 v[26:27], v[26:27], v[112:113] op_sel_hi:[1,0]
	v_pk_mul_f32 v[24:25], v[24:25], v[112:113] op_sel_hi:[1,0]
	v_pk_mul_f32 v[22:23], v[22:23], v[112:113] op_sel_hi:[1,0]
	v_pk_mul_f32 v[20:21], v[20:21], v[112:113] op_sel_hi:[1,0]
	v_pk_mul_f32 v[18:19], v[18:19], v[112:113] op_sel_hi:[1,0]
	v_pk_mul_f32 v[16:17], v[16:17], v[112:113] op_sel_hi:[1,0]
	v_pk_mul_f32 v[14:15], v[14:15], v[112:113] op_sel_hi:[1,0]
	v_pk_mul_f32 v[12:13], v[12:13], v[112:113] op_sel_hi:[1,0]
	v_pk_mul_f32 v[10:11], v[10:11], v[112:113] op_sel_hi:[1,0]
	v_pk_mul_f32 v[8:9], v[8:9], v[112:113] op_sel_hi:[1,0]
	v_pk_mul_f32 v[6:7], v[6:7], v[112:113] op_sel_hi:[1,0]
	v_pk_mul_f32 v[4:5], v[4:5], v[112:113] op_sel_hi:[1,0]
	v_pk_mul_f32 v[2:3], v[2:3], v[112:113] op_sel_hi:[1,0]
	v_pk_mul_f32 v[0:1], v[0:1], v[112:113] op_sel_hi:[1,0]
	v_sub_f32_e32 v80, v80, v242
	v_sub_f32_e32 v81, v81, v242
	v_sub_f32_e32 v82, v82, v242
	v_sub_f32_e32 v83, v83, v242
	v_sub_f32_e32 v84, v84, v242
	v_sub_f32_e32 v85, v85, v242
	v_sub_f32_e32 v86, v86, v242
	v_sub_f32_e32 v87, v87, v242
	v_sub_f32_e32 v88, v88, v242
	v_sub_f32_e32 v89, v89, v242
	v_sub_f32_e32 v90, v90, v242
	v_sub_f32_e32 v91, v91, v242
	v_sub_f32_e32 v92, v92, v242
	v_sub_f32_e32 v93, v93, v242
	v_sub_f32_e32 v94, v94, v242
	v_sub_f32_e32 v95, v95, v242
	v_sub_f32_e32 v64, v64, v242
	v_sub_f32_e32 v65, v65, v242
	v_sub_f32_e32 v66, v66, v242
	v_sub_f32_e32 v67, v67, v242
	v_sub_f32_e32 v68, v68, v242
	v_sub_f32_e32 v69, v69, v242
	v_sub_f32_e32 v70, v70, v242
	v_sub_f32_e32 v71, v71, v242
	v_sub_f32_e32 v72, v72, v242
	v_sub_f32_e32 v73, v73, v242
	v_sub_f32_e32 v74, v74, v242
	v_sub_f32_e32 v75, v75, v242
	v_sub_f32_e32 v76, v76, v242
	v_sub_f32_e32 v77, v77, v242
	v_sub_f32_e32 v78, v78, v242
	v_sub_f32_e32 v79, v79, v242
	v_sub_f32_e32 v226, v226, v242
	v_sub_f32_e32 v227, v227, v242
	v_sub_f32_e32 v228, v228, v242
	v_sub_f32_e32 v229, v229, v242
	v_sub_f32_e32 v230, v230, v242
	v_sub_f32_e32 v231, v231, v242
	v_sub_f32_e32 v232, v232, v242
	v_sub_f32_e32 v233, v233, v242
	v_sub_f32_e32 v234, v234, v242
	v_sub_f32_e32 v235, v235, v242
	v_sub_f32_e32 v236, v236, v242
	v_sub_f32_e32 v237, v237, v242
	v_sub_f32_e32 v238, v238, v242
	v_sub_f32_e32 v239, v239, v242
	v_sub_f32_e32 v240, v240, v242
	v_sub_f32_e32 v241, v241, v242
	s_branch .LBB0_133
